# GEMM K-loop (swiglu variant only): LDS-DMA loads rebalanced 4+4 between SP1 and SP2 load segments instead of 2+6 (A half-0 tile staged one segment later), SP2 waits vmcnt(4)
# speedup vs baseline: 1.0848x; 1.0848x over previous
; #define PG8_STAGE(bufoff, gbase, voff) do { _Pragma("unroll") for (int _i = 0; _i < 2; ++_i) \
;         __builtin_amdgcn_global_load_lds((const unsigned*)((const char*)(gbase) + (voff)[_i]), (PG8_LAS unsigned*)(lds + (bufoff) + ldsw + _i * 8192), 16, 0, 0); } while (0)
; #define PG8_LDA(dst, b, h) do { _Pragma("unroll") for (int m = 0; m < 4; ++m) _Pragma("unroll") for (int k = 0; k < 2; ++k) dst[m][k] = *(const PG8_LAS bf16x8*)(lds + PG8_SA(b, h) + aoff + m * 2048 + k * 1024); } while (0)
; #define PG8_LDB(dst, b, h) do { _Pragma("unroll") for (int n = 0; n < 2; ++n) _Pragma("unroll") for (int k = 0; k < 2; ++k) dst[n][k] = *(const PG8_LAS bf16x8*)(lds + PG8_SB(b, h) + boff + n * 2048 + k * 1024); } while (0)
; #define PG8_MMA(ai, bj, At, Bt) do { __builtin_amdgcn_s_setprio(1); _Pragma("unroll") for (int m = 0; m < 4; ++m) _Pragma("unroll") for (int n = 0; n < 2; ++n) _Pragma("unroll") for (int k = 0; k < 2; ++k) \
;         acc[ai][bj][m][n] = __builtin_amdgcn_mfma_f32_16x16x32_bf16(Bt[n][k], At[m][k], acc[ai][bj][m][n], 0, 0, 0); __builtin_amdgcn_s_setprio(0); } while (0)
; #define PG8_WAIT_V(n) asm volatile("s_waitcnt vmcnt(" #n ")" ::: "memory")
; #define PG8_WAIT_L(n) asm volatile("s_waitcnt lgkmcnt(" #n ")" ::: "memory")
; #define PG8_BAR __builtin_amdgcn_s_barrier()
; #define PG8_SCHED __builtin_amdgcn_sched_barrier(0)
; template <class Epi, class Sched, bool ALIGN_EPI = false, bool SP2 = false>
; __device__ __forceinline__ void gemm_phase(PG8_LAS unsigned char* lds, const Gemm g, const Sched& S, const Epi& E) {
;     ...
;             PG8_LDB(B0, 0, 0); PG8_LDB(B1, 0, 1); PG8_SCHED; PG8_LDA(At, 0, 0); PG8_STAGE(PG8_SA(1, 1), a1 + hstep, voffA);
;             PG8_WAIT_V(8); PG8_WAIT_L(0); PG8_BAR; PG8_MMA(0, 0, At, B0); PG8_MMA(0, 1, At, B1); PG8_BAR; PG8_SCHED;
;             PG8_LDA(At, 0, 1); PG8_STAGE(PG8_SB(0, 0), b2, voffB); PG8_STAGE(PG8_SB(0, 1), b2 + hstep, voffB); PG8_STAGE(PG8_SA(0, 0), a2, voffA);
;             PG8_WAIT_V(8); PG8_WAIT_L(0); PG8_BAR; PG8_MMA(1, 0, At, B0); PG8_MMA(1, 1, At, B1); PG8_BAR; PG8_SCHED;
.LBB0_417:
	s_add_u32 s0, s40, 0xfff80080
	s_addc_u32 s1, s41, -1
	s_add_i32 s30, 0, 0x10000
	s_cmp_eq_u32 s19, 28
	s_cselect_b32 s5, s7, s1
	s_cselect_b32 s4, s8, s0
	s_cselect_b32 s1, s9, s17
	s_cselect_b32 s0, s14, s15
	s_add_i32 s33, 0, 0x14000
	v_add_u32_e32 v142, s30, v203
	v_add_u32_e32 v158, s33, v203
	ds_read_b128 v[130:133], v142
	ds_read_b128 v[134:137], v142 offset:1024
	ds_read_b128 v[138:141], v142 offset:2048
	ds_read_b128 v[142:145], v142 offset:3072
	ds_read_b128 v[146:149], v158
	ds_read_b128 v[150:153], v158 offset:1024
	ds_read_b128 v[154:157], v158 offset:2048
	ds_read_b128 v[158:161], v158 offset:3072
	v_lshl_add_u64 v[190:191], s[40:41], 0, v[188:189]
	s_add_i32 m0, s67, 0xc000
	ds_read_b128 v[162:165], v209
	ds_read_b128 v[166:169], v209 offset:1024
	ds_read_b128 v[170:173], v209 offset:2048
	ds_read_b128 v[174:177], v209 offset:3072
	ds_read_b128 v[210:213], v209 offset:4096
	ds_read_b128 v[232:235], v209 offset:5120
	ds_read_b128 v[242:245], v209 offset:6144
	ds_read_b128 v[246:249], v209 offset:7168
	global_load_lds_dwordx4 v[190:191], off
	v_lshl_add_u64 v[190:191], s[40:41], 0, v[186:187]
	s_add_i32 m0, s67, 0xe000
	s_nop 0
	global_load_lds_dwordx4 v[190:191], off
	s_add_u32 vcc_lo, s40, 0xfff80000
	s_addc_u32 vcc_hi, s41, -1
	v_lshl_add_u64 v[190:191], vcc, 0, v[188:189]
	s_mov_b32 m0, s74
	s_nop 0
	global_load_lds_dwordx4 v[190:191], off
	v_lshl_add_u64 v[190:191], vcc, 0, v[186:187]
	s_mov_b32 m0, s75
	s_nop 0
	global_load_lds_dwordx4 v[190:191], off
	s_waitcnt vmcnt(8)
	s_waitcnt lgkmcnt(0)
	s_barrier
	v_mfma_f32_16x16x32_bf16 v[126:129], v[130:133], v[162:165], v[126:129]
	v_mfma_f32_16x16x32_bf16 v[122:125], v[138:141], v[162:165], v[122:125]
	v_mfma_f32_16x16x32_bf16 v[110:113], v[130:133], v[170:173], v[110:113]
	v_mfma_f32_16x16x32_bf16 v[106:109], v[138:141], v[170:173], v[106:109]
	v_mfma_f32_16x16x32_bf16 v[92:95], v[130:133], v[210:213], v[92:95]
	v_mfma_f32_16x16x32_bf16 v[88:91], v[138:141], v[210:213], v[88:91]
	v_mfma_f32_16x16x32_bf16 v[76:79], v[130:133], v[242:245], v[76:79]
	v_mfma_f32_16x16x32_bf16 v[72:75], v[138:141], v[242:245], v[72:75]
	v_mfma_f32_16x16x32_bf16 v[126:129], v[134:137], v[166:169], v[126:129]
	v_mfma_f32_16x16x32_bf16 v[122:125], v[142:145], v[166:169], v[122:125]
	v_mfma_f32_16x16x32_bf16 v[110:113], v[134:137], v[174:177], v[110:113]
	v_mfma_f32_16x16x32_bf16 v[106:109], v[142:145], v[174:177], v[106:109]
	v_mfma_f32_16x16x32_bf16 v[92:95], v[134:137], v[232:235], v[92:95]
	v_mfma_f32_16x16x32_bf16 v[88:91], v[142:145], v[232:235], v[88:91]
	v_mfma_f32_16x16x32_bf16 v[76:79], v[134:137], v[246:249], v[76:79]
	v_mfma_f32_16x16x32_bf16 v[72:75], v[142:145], v[246:249], v[72:75]
	v_mfma_f32_16x16x32_bf16 v[118:121], v[146:149], v[162:165], v[118:121]
	v_mfma_f32_16x16x32_bf16 v[114:117], v[154:157], v[162:165], v[114:117]
	v_mfma_f32_16x16x32_bf16 v[102:105], v[146:149], v[170:173], v[102:105]
	v_mfma_f32_16x16x32_bf16 v[98:101], v[154:157], v[170:173], v[98:101]
	v_mfma_f32_16x16x32_bf16 v[84:87], v[146:149], v[210:213], v[84:87]
	v_mfma_f32_16x16x32_bf16 v[80:83], v[154:157], v[210:213], v[80:83]
	v_mfma_f32_16x16x32_bf16 v[68:71], v[146:149], v[242:245], v[68:71]
	v_mfma_f32_16x16x32_bf16 v[64:67], v[154:157], v[242:245], v[64:67]
	v_mfma_f32_16x16x32_bf16 v[118:121], v[150:153], v[166:169], v[118:121]
	v_mfma_f32_16x16x32_bf16 v[114:117], v[158:161], v[166:169], v[114:117]
	v_mfma_f32_16x16x32_bf16 v[102:105], v[150:153], v[174:177], v[102:105]
	v_mfma_f32_16x16x32_bf16 v[98:101], v[158:161], v[174:177], v[98:101]
	v_mfma_f32_16x16x32_bf16 v[84:87], v[150:153], v[232:235], v[84:87]
	v_mfma_f32_16x16x32_bf16 v[80:83], v[158:161], v[232:235], v[80:83]
	v_mfma_f32_16x16x32_bf16 v[68:71], v[150:153], v[246:249], v[68:71]
	v_mfma_f32_16x16x32_bf16 v[64:67], v[158:161], v[246:249], v[64:67]
	s_barrier
	s_add_i32 s30, s30, s28
	v_lshl_add_u64 v[190:191], s[0:1], 0, v[96:97]
	s_mov_b32 m0, s30
	ds_read_b128 v[162:165], v209 offset:16384
	ds_read_b128 v[166:169], v209 offset:17408
	ds_read_b128 v[170:173], v209 offset:18432
	ds_read_b128 v[174:177], v209 offset:19456
	ds_read_b128 v[210:213], v209 offset:20480
	ds_read_b128 v[232:235], v209 offset:21504
	ds_read_b128 v[242:245], v209 offset:22528
	ds_read_b128 v[246:249], v209 offset:23552
	global_load_lds_dwordx4 v[190:191], off
	s_add_i32 m0, s30, 0x2000
	s_add_u32 s30, s0, 0x80000
	v_lshl_add_u64 v[204:205], s[0:1], 0, v[178:179]
	s_addc_u32 s31, s1, 0
	s_add_i32 s33, s33, s28
	global_load_lds_dwordx4 v[204:205], off
	v_lshl_add_u64 v[214:215], s[30:31], 0, v[96:97]
	s_mov_b32 m0, s33
	v_lshl_add_u64 v[228:229], s[4:5], 0, v[180:181]
	global_load_lds_dwordx4 v[214:215], off
	v_lshl_add_u64 v[214:215], s[30:31], 0, v[178:179]
	s_add_i32 m0, s33, 0x2000
	s_nop 0
	global_load_lds_dwordx4 v[214:215], off
	v_lshl_add_u64 v[214:215], s[4:5], 0, v[182:183]
	s_waitcnt vmcnt(4)
	s_waitcnt lgkmcnt(0)
	s_barrier
; #define PG8_STAGE(bufoff, gbase, voff) do { _Pragma("unroll") for (int _i = 0; _i < 2; ++_i) \
;         __builtin_amdgcn_global_load_lds((const unsigned*)((const char*)(gbase) + (voff)[_i]), (PG8_LAS unsigned*)(lds + (bufoff) + ldsw + _i * 8192), 16, 0, 0); } while (0)
; #define PG8_LDA(dst, b, h) do { _Pragma("unroll") for (int m = 0; m < 4; ++m) _Pragma("unroll") for (int k = 0; k < 2; ++k) dst[m][k] = *(const PG8_LAS bf16x8*)(lds + PG8_SA(b, h) + aoff + m * 2048 + k * 1024); } while (0)
; #define PG8_LDB(dst, b, h) do { _Pragma("unroll") for (int n = 0; n < 2; ++n) _Pragma("unroll") for (int k = 0; k < 2; ++k) dst[n][k] = *(const PG8_LAS bf16x8*)(lds + PG8_SB(b, h) + boff + n * 2048 + k * 1024); } while (0)
; #define PG8_MMA(ai, bj, At, Bt) do { __builtin_amdgcn_s_setprio(1); _Pragma("unroll") for (int m = 0; m < 4; ++m) _Pragma("unroll") for (int n = 0; n < 2; ++n) _Pragma("unroll") for (int k = 0; k < 2; ++k) \
;         acc[ai][bj][m][n] = __builtin_amdgcn_mfma_f32_16x16x32_bf16(Bt[n][k], At[m][k], acc[ai][bj][m][n], 0, 0, 0); __builtin_amdgcn_s_setprio(0); } while (0)
; #define PG8_WAIT_V(n) asm volatile("s_waitcnt vmcnt(" #n ")" ::: "memory")
; #define PG8_WAIT_L(n) asm volatile("s_waitcnt lgkmcnt(" #n ")" ::: "memory")
; #define PG8_BAR __builtin_amdgcn_s_barrier()
; #define PG8_SCHED __builtin_amdgcn_sched_barrier(0)
; template <class Epi, class Sched, bool ALIGN_EPI = false, bool SP2 = false>
; __device__ __forceinline__ void gemm_phase(PG8_LAS unsigned char* lds, const Gemm g, const Sched& S, const Epi& E) {
;     ...
;             PG8_WAIT_V(8); PG8_WAIT_L(0); PG8_BAR; PG8_MMA(1, 0, At, B0); PG8_MMA(1, 1, At, B1); PG8_BAR; PG8_SCHED;
;             PG8_LDB(B0, 1, 0); PG8_LDB(B1, 1, 1); PG8_SCHED; PG8_LDA(At, 1, 0); PG8_STAGE(PG8_SA(0, 1), a2 + hstep, voffA);
;             PG8_WAIT_V(8); PG8_WAIT_L(0); PG8_BAR; PG8_MMA(0, 0, At, B0); PG8_MMA(0, 1, At, B1); PG8_BAR; PG8_SCHED;
	v_mfma_f32_16x16x32_bf16 v[60:63], v[130:133], v[162:165], v[60:63]
	v_mfma_f32_16x16x32_bf16 v[56:59], v[138:141], v[162:165], v[56:59]
	v_mfma_f32_16x16x32_bf16 v[44:47], v[130:133], v[170:173], v[44:47]
	v_mfma_f32_16x16x32_bf16 v[40:43], v[138:141], v[170:173], v[40:43]
	v_mfma_f32_16x16x32_bf16 v[28:31], v[130:133], v[210:213], v[28:31]
	v_mfma_f32_16x16x32_bf16 v[24:27], v[138:141], v[210:213], v[24:27]
	v_mfma_f32_16x16x32_bf16 v[12:15], v[130:133], v[242:245], v[12:15]
	v_mfma_f32_16x16x32_bf16 v[8:11], v[138:141], v[242:245], v[8:11]
	v_mfma_f32_16x16x32_bf16 v[60:63], v[134:137], v[166:169], v[60:63]
	v_mfma_f32_16x16x32_bf16 v[56:59], v[142:145], v[166:169], v[56:59]
	v_mfma_f32_16x16x32_bf16 v[44:47], v[134:137], v[174:177], v[44:47]
	v_mfma_f32_16x16x32_bf16 v[40:43], v[142:145], v[174:177], v[40:43]
	v_mfma_f32_16x16x32_bf16 v[28:31], v[134:137], v[232:235], v[28:31]
	v_mfma_f32_16x16x32_bf16 v[24:27], v[142:145], v[232:235], v[24:27]
	v_mfma_f32_16x16x32_bf16 v[12:15], v[134:137], v[246:249], v[12:15]
	v_mfma_f32_16x16x32_bf16 v[8:11], v[142:145], v[246:249], v[8:11]
	v_mfma_f32_16x16x32_bf16 v[52:55], v[146:149], v[162:165], v[52:55]
	v_mfma_f32_16x16x32_bf16 v[48:51], v[154:157], v[162:165], v[48:51]
	v_mfma_f32_16x16x32_bf16 v[36:39], v[146:149], v[170:173], v[36:39]
	v_mfma_f32_16x16x32_bf16 v[32:35], v[154:157], v[170:173], v[32:35]
	v_mfma_f32_16x16x32_bf16 v[20:23], v[146:149], v[210:213], v[20:23]
	v_mfma_f32_16x16x32_bf16 v[16:19], v[154:157], v[210:213], v[16:19]
	v_mfma_f32_16x16x32_bf16 v[4:7], v[146:149], v[242:245], v[4:7]
	v_mfma_f32_16x16x32_bf16 v[0:3], v[154:157], v[242:245], v[0:3]
	v_mfma_f32_16x16x32_bf16 v[52:55], v[150:153], v[166:169], v[52:55]
	v_mfma_f32_16x16x32_bf16 v[48:51], v[158:161], v[166:169], v[48:51]
	v_mfma_f32_16x16x32_bf16 v[36:39], v[150:153], v[174:177], v[36:39]
	v_mfma_f32_16x16x32_bf16 v[32:35], v[158:161], v[174:177], v[32:35]
	v_mfma_f32_16x16x32_bf16 v[20:23], v[150:153], v[232:235], v[20:23]
	v_mfma_f32_16x16x32_bf16 v[16:19], v[158:161], v[232:235], v[16:19]
	v_mfma_f32_16x16x32_bf16 v[4:7], v[150:153], v[246:249], v[4:7]
	v_mfma_f32_16x16x32_bf16 v[0:3], v[158:161], v[246:249], v[0:3]
	s_barrier
	s_add_i32 s30, 0, 0x18000
	s_add_i32 s31, 0, 0x1c000
	v_add_u32_e32 v142, s30, v203
	v_add_u32_e32 v158, s31, v203
	ds_read_b128 v[130:133], v142
	ds_read_b128 v[134:137], v142 offset:1024
	ds_read_b128 v[138:141], v142 offset:2048
	ds_read_b128 v[142:145], v142 offset:3072
	ds_read_b128 v[146:149], v158
	ds_read_b128 v[150:153], v158 offset:1024
	ds_read_b128 v[154:157], v158 offset:2048
	ds_read_b128 v[158:161], v158 offset:3072
	s_mov_b32 m0, s67
	s_nop 0
	global_load_lds_dwordx4 v[214:215], off
	s_mov_b32 m0, s68
	s_nop 0
	global_load_lds_dwordx4 v[228:229], off
	s_add_u32 s4, s4, 0x80000
	s_addc_u32 s5, s5, 0
	s_mov_b32 m0, s69
	v_lshl_add_u64 v[230:231], s[4:5], 0, v[182:183]
	ds_read_b128 v[162:165], v209 offset:32768
	ds_read_b128 v[166:169], v209 offset:33792
	ds_read_b128 v[170:173], v209 offset:34816
	ds_read_b128 v[174:177], v209 offset:35840
	ds_read_b128 v[210:213], v209 offset:36864
	ds_read_b128 v[232:235], v209 offset:37888
	ds_read_b128 v[242:245], v209 offset:38912
	ds_read_b128 v[246:249], v209 offset:39936
	global_load_lds_dwordx4 v[230:231], off
	v_lshl_add_u64 v[230:231], s[4:5], 0, v[180:181]
	s_mov_b32 m0, s72
	s_nop 0
	global_load_lds_dwordx4 v[230:231], off
	s_waitcnt vmcnt(8)
	s_waitcnt lgkmcnt(0)
	s_barrier
; #define PG8_STAGE(bufoff, gbase, voff) do { _Pragma("unroll") for (int _i = 0; _i < 2; ++_i) \
;         __builtin_amdgcn_global_load_lds((const unsigned*)((const char*)(gbase) + (voff)[_i]), (PG8_LAS unsigned*)(lds + (bufoff) + ldsw + _i * 8192), 16, 0, 0); } while (0)
; #define PG8_LDA(dst, b, h) do { _Pragma("unroll") for (int m = 0; m < 4; ++m) _Pragma("unroll") for (int k = 0; k < 2; ++k) dst[m][k] = *(const PG8_LAS bf16x8*)(lds + PG8_SA(b, h) + aoff + m * 2048 + k * 1024); } while (0)
; #define PG8_MMA(ai, bj, At, Bt) do { __builtin_amdgcn_s_setprio(1); _Pragma("unroll") for (int m = 0; m < 4; ++m) _Pragma("unroll") for (int n = 0; n < 2; ++n) _Pragma("unroll") for (int k = 0; k < 2; ++k) \
;         acc[ai][bj][m][n] = __builtin_amdgcn_mfma_f32_16x16x32_bf16(Bt[n][k], At[m][k], acc[ai][bj][m][n], 0, 0, 0); __builtin_amdgcn_s_setprio(0); } while (0)
; #define PG8_WAIT_V(n) asm volatile("s_waitcnt vmcnt(" #n ")" ::: "memory")
; #define PG8_WAIT_L(n) asm volatile("s_waitcnt lgkmcnt(" #n ")" ::: "memory")
; #define PG8_BAR __builtin_amdgcn_s_barrier()
; #define PG8_SCHED __builtin_amdgcn_sched_barrier(0)
; template <class Epi, class Sched, bool ALIGN_EPI = false, bool SP2 = false>
; __device__ __forceinline__ void gemm_phase(PG8_LAS unsigned char* lds, const Gemm g, const Sched& S, const Epi& E) {
;     ...
;             PG8_WAIT_V(8); PG8_WAIT_L(0); PG8_BAR; PG8_MMA(0, 0, At, B0); PG8_MMA(0, 1, At, B1); PG8_BAR; PG8_SCHED;
;             PG8_LDA(At, 1, 1); PG8_STAGE(PG8_SB(1, 0), b3, voffB); PG8_STAGE(PG8_SB(1, 1), b3 + hstep, voffB); PG8_STAGE(PG8_SA(1, 0), a3, voffA);
;             PG8_WAIT_V(8); PG8_WAIT_L(0); PG8_BAR; PG8_MMA(1, 0, At, B0); PG8_MMA(1, 1, At, B1); PG8_BAR; PG8_SCHED;
	v_mfma_f32_16x16x32_bf16 v[126:129], v[130:133], v[162:165], v[126:129]
	v_mfma_f32_16x16x32_bf16 v[122:125], v[138:141], v[162:165], v[122:125]
	v_mfma_f32_16x16x32_bf16 v[110:113], v[130:133], v[170:173], v[110:113]
	v_mfma_f32_16x16x32_bf16 v[106:109], v[138:141], v[170:173], v[106:109]
	v_mfma_f32_16x16x32_bf16 v[92:95], v[130:133], v[210:213], v[92:95]
	v_mfma_f32_16x16x32_bf16 v[88:91], v[138:141], v[210:213], v[88:91]
	v_mfma_f32_16x16x32_bf16 v[76:79], v[130:133], v[242:245], v[76:79]
	v_mfma_f32_16x16x32_bf16 v[72:75], v[138:141], v[242:245], v[72:75]
	v_mfma_f32_16x16x32_bf16 v[126:129], v[134:137], v[166:169], v[126:129]
	v_mfma_f32_16x16x32_bf16 v[122:125], v[142:145], v[166:169], v[122:125]
	v_mfma_f32_16x16x32_bf16 v[110:113], v[134:137], v[174:177], v[110:113]
	v_mfma_f32_16x16x32_bf16 v[106:109], v[142:145], v[174:177], v[106:109]
	v_mfma_f32_16x16x32_bf16 v[92:95], v[134:137], v[232:235], v[92:95]
	v_mfma_f32_16x16x32_bf16 v[88:91], v[142:145], v[232:235], v[88:91]
	v_mfma_f32_16x16x32_bf16 v[76:79], v[134:137], v[246:249], v[76:79]
	v_mfma_f32_16x16x32_bf16 v[72:75], v[142:145], v[246:249], v[72:75]
	v_mfma_f32_16x16x32_bf16 v[118:121], v[146:149], v[162:165], v[118:121]
	v_mfma_f32_16x16x32_bf16 v[114:117], v[154:157], v[162:165], v[114:117]
	v_mfma_f32_16x16x32_bf16 v[102:105], v[146:149], v[170:173], v[102:105]
	v_mfma_f32_16x16x32_bf16 v[98:101], v[154:157], v[170:173], v[98:101]
	v_mfma_f32_16x16x32_bf16 v[84:87], v[146:149], v[210:213], v[84:87]
	v_mfma_f32_16x16x32_bf16 v[80:83], v[154:157], v[210:213], v[80:83]
	v_mfma_f32_16x16x32_bf16 v[68:71], v[146:149], v[242:245], v[68:71]
	v_mfma_f32_16x16x32_bf16 v[64:67], v[154:157], v[242:245], v[64:67]
	v_mfma_f32_16x16x32_bf16 v[118:121], v[150:153], v[166:169], v[118:121]
	v_mfma_f32_16x16x32_bf16 v[114:117], v[158:161], v[166:169], v[114:117]
	v_mfma_f32_16x16x32_bf16 v[102:105], v[150:153], v[174:177], v[102:105]
	v_mfma_f32_16x16x32_bf16 v[98:101], v[158:161], v[174:177], v[98:101]
	v_mfma_f32_16x16x32_bf16 v[84:87], v[150:153], v[232:235], v[84:87]
	v_mfma_f32_16x16x32_bf16 v[80:83], v[158:161], v[232:235], v[80:83]
	v_mfma_f32_16x16x32_bf16 v[68:71], v[150:153], v[246:249], v[68:71]
	v_mfma_f32_16x16x32_bf16 v[64:67], v[158:161], v[246:249], v[64:67]
	s_barrier
	s_add_i32 s4, s30, s28
	v_lshl_add_u64 v[190:191], v[190:191], 0, s[20:21]
	s_mov_b32 m0, s4
	ds_read_b128 v[162:165], v209 offset:49152
	ds_read_b128 v[166:169], v209 offset:50176
	ds_read_b128 v[170:173], v209 offset:51200
	ds_read_b128 v[174:177], v209 offset:52224
	ds_read_b128 v[210:213], v209 offset:53248
	ds_read_b128 v[232:235], v209 offset:54272
	ds_read_b128 v[242:245], v209 offset:55296
	ds_read_b128 v[246:249], v209 offset:56320
	global_load_lds_dwordx4 v[190:191], off
	s_add_i32 m0, s4, 0x2000
	s_add_u32 s0, s0, 0x80080
	v_lshl_add_u64 v[190:191], v[204:205], 0, s[20:21]
	s_addc_u32 s1, s1, 0
	s_add_i32 s4, s31, s28
	global_load_lds_dwordx4 v[190:191], off
	v_lshl_add_u64 v[190:191], s[0:1], 0, v[96:97]
	s_mov_b32 m0, s4
	s_nop 0
	global_load_lds_dwordx4 v[190:191], off
	v_lshl_add_u64 v[190:191], s[0:1], 0, v[178:179]
	s_add_i32 m0, s4, 0x2000
	s_nop 0
	global_load_lds_dwordx4 v[190:191], off
	s_waitcnt vmcnt(4)
	s_waitcnt lgkmcnt(0)
	s_barrier
	v_mfma_f32_16x16x32_bf16 v[60:63], v[130:133], v[162:165], v[60:63]
	v_mfma_f32_16x16x32_bf16 v[56:59], v[138:141], v[162:165], v[56:59]
	v_mfma_f32_16x16x32_bf16 v[44:47], v[130:133], v[170:173], v[44:47]
	v_mfma_f32_16x16x32_bf16 v[40:43], v[138:141], v[170:173], v[40:43]
	v_mfma_f32_16x16x32_bf16 v[28:31], v[130:133], v[210:213], v[28:31]
	v_mfma_f32_16x16x32_bf16 v[24:27], v[138:141], v[210:213], v[24:27]
	v_mfma_f32_16x16x32_bf16 v[12:15], v[130:133], v[242:245], v[12:15]
	v_mfma_f32_16x16x32_bf16 v[8:11], v[138:141], v[242:245], v[8:11]
	v_mfma_f32_16x16x32_bf16 v[60:63], v[134:137], v[166:169], v[60:63]
	v_mfma_f32_16x16x32_bf16 v[56:59], v[142:145], v[166:169], v[56:59]
	v_mfma_f32_16x16x32_bf16 v[44:47], v[134:137], v[174:177], v[44:47]
	v_mfma_f32_16x16x32_bf16 v[40:43], v[142:145], v[174:177], v[40:43]
	v_mfma_f32_16x16x32_bf16 v[28:31], v[134:137], v[232:235], v[28:31]
	v_mfma_f32_16x16x32_bf16 v[24:27], v[142:145], v[232:235], v[24:27]
	v_mfma_f32_16x16x32_bf16 v[12:15], v[134:137], v[246:249], v[12:15]
	v_mfma_f32_16x16x32_bf16 v[8:11], v[142:145], v[246:249], v[8:11]
	v_mfma_f32_16x16x32_bf16 v[52:55], v[146:149], v[162:165], v[52:55]
	v_mfma_f32_16x16x32_bf16 v[48:51], v[154:157], v[162:165], v[48:51]
	v_mfma_f32_16x16x32_bf16 v[36:39], v[146:149], v[170:173], v[36:39]
	v_mfma_f32_16x16x32_bf16 v[32:35], v[154:157], v[170:173], v[32:35]
	v_mfma_f32_16x16x32_bf16 v[20:23], v[146:149], v[210:213], v[20:23]
	v_mfma_f32_16x16x32_bf16 v[16:19], v[154:157], v[210:213], v[16:19]
	v_mfma_f32_16x16x32_bf16 v[4:7], v[146:149], v[242:245], v[4:7]
	v_mfma_f32_16x16x32_bf16 v[0:3], v[154:157], v[242:245], v[0:3]
	v_mfma_f32_16x16x32_bf16 v[52:55], v[150:153], v[166:169], v[52:55]
	v_mfma_f32_16x16x32_bf16 v[48:51], v[158:161], v[166:169], v[48:51]
	v_mfma_f32_16x16x32_bf16 v[36:39], v[150:153], v[174:177], v[36:39]
	v_mfma_f32_16x16x32_bf16 v[32:35], v[158:161], v[174:177], v[32:35]
	v_mfma_f32_16x16x32_bf16 v[20:23], v[150:153], v[232:235], v[20:23]
	v_mfma_f32_16x16x32_bf16 v[16:19], v[158:161], v[232:235], v[16:19]
	v_mfma_f32_16x16x32_bf16 v[4:7], v[150:153], v[246:249], v[4:7]
	v_mfma_f32_16x16x32_bf16 v[0:3], v[158:161], v[246:249], v[0:3]
	s_barrier
	s_add_i32 s19, s19, 2
	s_add_u32 s15, s15, 0x100
	s_addc_u32 s17, s17, 0
	s_add_u32 s40, s40, 0x100
	s_addc_u32 s41, s41, 0
	s_cmp_gt_u32 s19, 29
	s_cbranch_scc0 .LBB0_417
	s_and_b64 vcc, exec, s[34:35]
	s_cbranch_vccz .LBB0_420
	s_barrier
